# v88: v76 + half-tile rotation of waves 4-7 (second half of plain diff tiles deferred across the loop barrier, two barriers per tile)
# speedup vs baseline: 1.0105x; 1.0105x over previous
; #define ATT_WAITV(n) asm volatile("s_waitcnt vmcnt(" #n ")" ::: "memory")
; template <bool ONLINE, int NO>
; __device__ __forceinline__ void softmax_tile(f32x16 (&s)[2], float& m, float& l, f32x16 (&O)[NO], u32x4 (&pk)[4]) {
;     ...
;     float ps = 0.f;
; #pragma unroll
;     for (int blk = 0; blk < 2; ++blk)
; #pragma unroll
;         for (int i = 0; i < 16; ++i) { const float p = __builtin_amdgcn_exp2f(ONLINE ? (s[blk][i] - mn) : s[blk][i]); ps += p; s[blk][i] = p; }
;     l += ps;
; #pragma unroll
;     for (int blk = 0; blk < 2; ++blk)
; #pragma unroll
;         for (int sh = 0; sh < 2; ++sh) { u32x4 pw;
;             pw.x = cvt_pk_bf16(s[blk][8 * sh], s[blk][8 * sh + 1]); pw.y = cvt_pk_bf16(s[blk][8 * sh + 2], s[blk][8 * sh + 3]);
;             pw.z = cvt_pk_bf16(s[blk][8 * sh + 4], s[blk][8 * sh + 5]); pw.w = cvt_pk_bf16(s[blk][8 * sh + 6], s[blk][8 * sh + 7]); pk[2 * blk + sh] = pw; }
; template <int MODE>
; __device__ __forceinline__ void attn_unit(const Params& P, LAS unsigned char* lds, const int b, const int h, const int qb) {
;     ...
;     for (int kt = kt0; kt < nt; ++kt) {
;         const int rel = kt - kt0, cur = rel & (AL_NBUF - 1);
;         if (kt + 2 < nt) { if (FOX) ATT_WAITV(10); else ATT_WAITV(8); } else if (kt + 1 < nt) { if (FOX) ATT_WAITV(5); else ATT_WAITV(4); } else ATT_WAITV(0);
;         __builtin_amdgcn_s_barrier(); asm volatile("" ::: "memory");
;         if (kt + AL_PD < nt) ATT_DMA(kt + AL_PD, (rel + AL_PD) & (AL_NBUF - 1));
.LBB0_483:
	s_barrier
	s_cmpk_lt_u32 s58, 0x100
	s_cbranch_scc1 .LBB0_485
	s_cmp_eq_u32 s40, 0
	s_cbranch_scc1 .LmB_bar2
	s_add_i32 s41, s39, 0xffffff81
	s_cmp_le_i32 s41, s75
	s_cbranch_scc0 .LmB_bar2
	s_waitcnt lgkmcnt(8)
	v_mfma_f32_32x32x16_bf16 v[64:79], v[168:171], v[100:103], v[64:79]
	ds_read_b64_tr_b16 v[144:145], v0 offset:0x3000
	ds_read_b64_tr_b16 v[146:147], v0 offset:0x3100
	ds_read_b64_tr_b16 v[140:141], v0 offset:0x3200
	ds_read_b64_tr_b16 v[142:143], v0 offset:0x3300
	ds_read_b64_tr_b16 v[136:137], v0 offset:0x3400
	ds_read_b64_tr_b16 v[138:139], v0 offset:0x3500
	ds_read_b64_tr_b16 v[132:133], v0 offset:0x3600
	ds_read_b64_tr_b16 v[134:135], v0 offset:0x3700
	v_mfma_f32_32x32x16_bf16 v[48:63], v[10:13], v[100:103], v[48:63]
	v_exp_f32_e32 v104, v80
	v_exp_f32_e32 v105, v81
	v_exp_f32_e32 v106, v82
	v_mfma_f32_32x32x16_bf16 v[32:47], v[180:183], v[100:103], v[32:47]
	v_exp_f32_e32 v107, v83
	v_exp_f32_e32 v108, v84
	v_exp_f32_e32 v109, v85
	v_mfma_f32_32x32x16_bf16 v[16:31], v[2:5], v[100:103], v[16:31]
	v_exp_f32_e32 v110, v86
	v_exp_f32_e32 v111, v87
	v_cvt_pk_bf16_f32 v80, v104, v105
	v_cvt_pk_bf16_f32 v81, v106, v107
	v_cvt_pk_bf16_f32 v82, v108, v109
	v_add_f32_e32 v14, v242, v14
	v_cvt_pk_bf16_f32 v83, v110, v111
	v_add_f32_e32 v14, v243, v14
	s_waitcnt lgkmcnt(8)
	v_mfma_f32_32x32x16_bf16 v[64:79], v[6:9], v[80:83], v[64:79]
	v_exp_f32_e32 v2, v88
	v_exp_f32_e32 v3, v89
	v_exp_f32_e32 v4, v90
	v_mfma_f32_32x32x16_bf16 v[48:63], v[128:131], v[80:83], v[48:63]
	v_exp_f32_e32 v5, v91
	v_exp_f32_e32 v10, v92
	v_exp_f32_e32 v11, v93
	v_mfma_f32_32x32x16_bf16 v[32:47], v[172:175], v[80:83], v[32:47]
	v_exp_f32_e32 v12, v94
	v_exp_f32_e32 v13, v95
	v_add_f32_e32 v14, v244, v14
	v_add_f32_e32 v14, v245, v14
	v_mfma_f32_32x32x16_bf16 v[16:31], v[184:187], v[80:83], v[16:31]
	v_cvt_pk_bf16_f32 v84, v2, v3
	v_cvt_pk_bf16_f32 v85, v4, v5
	v_cvt_pk_bf16_f32 v86, v10, v11
	v_add_f32_e32 v14, v246, v14
	v_cvt_pk_bf16_f32 v87, v12, v13
	v_add_f32_e32 v14, v247, v14
	v_add_f32_e32 v14, v248, v14
	s_waitcnt lgkmcnt(0)
	v_add_f32_e32 v14, v249, v14
	v_add_f32_e32 v14, v250, v14
	v_add_f32_e32 v14, v251, v14
	v_add_f32_e32 v14, v252, v14
	v_add_f32_e32 v14, v253, v14
	v_mfma_f32_32x32x16_bf16 v[64:79], v[144:147], v[84:87], v[64:79]
	v_add_f32_e32 v14, v104, v14
	v_add_f32_e32 v14, v105, v14
	v_add_f32_e32 v14, v106, v14
	v_add_f32_e32 v14, v107, v14
	v_add_f32_e32 v14, v108, v14
	v_add_f32_e32 v14, v109, v14
	v_mfma_f32_32x32x16_bf16 v[48:63], v[140:143], v[84:87], v[48:63]
	v_add_f32_e32 v14, v110, v14
	v_add_f32_e32 v14, v111, v14
	v_add_f32_e32 v14, v2, v14
	v_add_f32_e32 v14, v3, v14
	v_add_f32_e32 v14, v4, v14
	v_add_f32_e32 v14, v5, v14
	v_mfma_f32_32x32x16_bf16 v[32:47], v[136:139], v[84:87], v[32:47]
	v_add_f32_e32 v14, v10, v14
	v_add_f32_e32 v14, v11, v14
	v_add_f32_e32 v14, v12, v14
	v_add_f32_e32 v14, v13, v14
	v_add_f32_e32 v163, v163, v14
	v_mfma_f32_32x32x16_bf16 v[16:31], v[132:135], v[84:87], v[16:31]


; #define LAS __attribute__((address_space(3)))
; template <int MODE>
; __device__ __forceinline__ void attn_unit(const Params& P, LAS unsigned char* lds, const int b, const int h, const int qb) {
;     ...
;         if (kt <= ktw_last) {
;             const LAS unsigned char* Kb = lds + cur * 32768;
.Lm1_slow:
	s_cmpk_gt_u32 s58, 0xff
	s_cbranch_scc1 .Lm1_slow2
	s_barrier

; template <int MODE>
; __device__ __forceinline__ void attn_unit(const Params& P, LAS unsigned char* lds, const int b, const int h, const int qb) {
;     ...
;             if constexpr (MODE == 1) {
;                 bf16x8 kf[8];
;                 const unsigned kb_ = (unsigned)(uintptr_t)Kb + kra, c0 = mp * 8 + hh;
;                 k_issue4(kf, kb_ + (((c0) ^ kswz) << 4), kb_ + (((c0 + 2) ^ kswz) << 4), kb_ + (((c0 + 4) ^ kswz) << 4), kb_ + (((c0 + 6) ^ kswz) << 4));
;                 v_issue<0>(va, vaddr);
;                 k_wait<8>(kf);
; #pragma unroll
;                 for (int ks = 0; ks < 4; ++ks) { s[0] = MFMA32(kf[2 * ks], Qf[ks], s[0]); s[1] = MFMA32(kf[2 * ks + 1], Qf[ks], s[1]); }
;                 v_issue<1>(vb, vaddr);
;             } else {
; #pragma unroll
;             for (int ks = 0; ks < NQ; ++ks) {
;                 const unsigned chunk = mp * 8 + 2 * ks + hh;
;                 const unsigned off = kra + ((chunk ^ kswz) << 4);
;                 const bf16x8 a0 = *(const LAS bf16x8*)(Kb + off), a1 = *(const LAS bf16x8*)(Kb + off + 8192);
;                 s[0] = MFMA32(a0, Qf[ks], s[0]); s[1] = MFMA32(a1, Qf[ks], s[1]);
;             }
;             v_issue<0>(va, vaddr);
;             }
;             if (FOX) {
;                 const LAS float* cl = (const LAS float*)(lds + AL_CLS + (cur * 8 + w) * 256) + 8 * hh;
; #pragma unroll
;                 for (int blk = 0; blk < 2; ++blk)
; #pragma unroll
;                     for (int j4 = 0; j4 < 4; ++j4) { const f32x4 c = *(const LAS f32x4*)(cl + 32 * blk + 16 * (j4 >> 1) + 4 * (j4 & 1));
; #pragma unroll
;                         for (int e = 0; e < 4; ++e) s[blk][4 * j4 + e] -= c[e]; }
;             } else if (q0w - kt * 64 - 63 < 128) {
;                 const LAS float* bl = (const LAS float*)(lds + AL_BIAS);
; #pragma unroll
;                 for (int blk = 0; blk < 2; ++blk)
; #pragma unroll
;                     for (int i = 0; i < 16; ++i) { const int dist = q - (kbase + 32 * blk + 16 * (i >> 3) + (i & 7)); const int di = dist < 0 ? 0 : (dist > 128 ? 128 : dist); s[blk][i] += bl[di]; }
;             }
;             if (kt * 64 + 63 > q0w) {
; #pragma unroll
;                 for (int blk = 0; blk < 2; ++blk)
; #pragma unroll
;                     for (int i = 0; i < 16; ++i) { if (kbase + 32 * blk + 16 * (i >> 3) + (i & 7) > q) s[blk][i] = -INFINITY; }
;             }
.Lm1_skip:
	s_cmpk_gt_u32 s58, 0xff
	s_cbranch_scc1 .LBB0_474
	s_barrier
	s_add_i32 s41, s40, 3
	s_cmp_ge_u32 s41, s22
	s_cbranch_scc1 .LBB0_474
	s_cmpk_gt_u32 s58, 0xff
	s_cbranch_scc1 .LBB0_474
	s_mov_b64 s[70:71], 0x1000
	s_add_i32 s41, s38, 0x18000
	s_and_b32 s41, s41, 0x18000
	s_add_i32 s41, s77, s41
	v_lshl_add_u64 v[2:3], v[152:153], 0, s[68:69]
	v_lshl_add_u64 v[4:5], v[2:3], 0, s[42:43]
	s_mov_b32 m0, s41
	v_lshl_add_u64 v[2:3], v[2:3], 0, s[44:45]
	global_load_lds_dwordx4 v[4:5], off
	s_add_i32 m0, s41, 0x1000
	v_lshl_add_u64 v[4:5], v[4:5], 0, s[70:71]
	global_load_lds_dwordx4 v[4:5], off
	s_add_i32 m0, s41, 0x2000
	v_lshl_add_u64 v[4:5], v[2:3], 0, s[70:71]
	global_load_lds_dwordx4 v[2:3], off
	s_add_i32 m0, s41, 0x3000
	v_lshl_add_u64 v[2:3], v[154:155], 0, s[68:69]
	global_load_lds_dwordx4 v[4:5], off
	v_lshl_add_u64 v[4:5], v[2:3], 0, s[48:49]
	s_add_i32 m0, s41, 0x4000
	v_lshl_add_u64 v[2:3], v[2:3], 0, s[50:51]
	global_load_lds_dwordx4 v[4:5], off
	s_add_i32 m0, s41, 0x5000
	v_lshl_add_u64 v[4:5], v[4:5], 0, s[70:71]
	global_load_lds_dwordx4 v[4:5], off
	s_add_i32 m0, s41, 0x6000
	v_lshl_add_u64 v[4:5], v[2:3], 0, s[70:71]
	global_load_lds_dwordx4 v[2:3], off
	s_add_i32 m0, s41, 0x7000
	s_nop 0
	global_load_lds_dwordx4 v[4:5], off
	s_branch .LBB0_474
.Lm1_fast:
	s_cmpk_lt_u32 s58, 0x100
	s_cbranch_scc0 .Lm1_fastB
	v_mfma_f32_32x32x16_bf16 v[96:111], v[2:5], v[112:115], 0
	v_mfma_f32_32x32x16_bf16 v[96:111], v[10:13], v[116:119], v[96:111]
	v_mfma_f32_32x32x16_bf16 v[96:111], v[168:171], v[120:123], v[96:111]
	v_mfma_f32_32x32x16_bf16 v[96:111], v[180:183], v[124:127], v[96:111]
	ds_read_b64_tr_b16 v[168:169], v0 offset:0x1000
	ds_read_b64_tr_b16 v[170:171], v0 offset:0x1100
	ds_read_b64_tr_b16 v[10:11], v0 offset:0x1200
	ds_read_b64_tr_b16 v[12:13], v0 offset:0x1300
	ds_read_b64_tr_b16 v[180:181], v0 offset:0x1400
	ds_read_b64_tr_b16 v[182:183], v0 offset:0x1500
	ds_read_b64_tr_b16 v[2:3], v0 offset:0x1600
	ds_read_b64_tr_b16 v[4:5], v0 offset:0x1700
	v_mfma_f32_32x32x16_bf16 v[80:95], v[6:9], v[112:115], 0
	s_nop 2
	v_exp_f32_e32 v14, v96
	v_exp_f32_e32 v15, v97
	v_mfma_f32_32x32x16_bf16 v[80:95], v[128:131], v[116:119], v[80:95]
	v_exp_f32_e32 v240, v98
	v_exp_f32_e32 v241, v99
	v_exp_f32_e32 v242, v100
	v_mfma_f32_32x32x16_bf16 v[80:95], v[172:175], v[120:123], v[80:95]
	v_exp_f32_e32 v243, v101
	v_exp_f32_e32 v244, v102
	v_exp_f32_e32 v245, v103
	v_mfma_f32_32x32x16_bf16 v[80:95], v[184:187], v[124:127], v[80:95]
	v_cvt_pk_bf16_f32 v96, v14, v15
	v_cvt_pk_bf16_f32 v97, v240, v241
	v_cvt_pk_bf16_f32 v98, v242, v243
	v_cvt_pk_bf16_f32 v99, v244, v245
	v_exp_f32_e32 v246, v104
	s_waitcnt lgkmcnt(8)
	v_mfma_f32_32x32x16_bf16 v[64:79], v[144:147], v[96:99], v[64:79]
	ds_read_b64_tr_b16 v[6:7], v0 offset:0x2000
	ds_read_b64_tr_b16 v[8:9], v0 offset:0x2100
	ds_read_b64_tr_b16 v[128:129], v0 offset:0x2200
	ds_read_b64_tr_b16 v[130:131], v0 offset:0x2300
	ds_read_b64_tr_b16 v[172:173], v0 offset:0x2400
	ds_read_b64_tr_b16 v[174:175], v0 offset:0x2500
	ds_read_b64_tr_b16 v[184:185], v0 offset:0x2600
	ds_read_b64_tr_b16 v[186:187], v0 offset:0x2700
	v_mfma_f32_32x32x16_bf16 v[48:63], v[140:143], v[96:99], v[48:63]
	v_exp_f32_e32 v247, v105
	v_exp_f32_e32 v248, v106
	v_exp_f32_e32 v249, v107
	v_mfma_f32_32x32x16_bf16 v[32:47], v[136:139], v[96:99], v[32:47]
	v_exp_f32_e32 v250, v108
	v_exp_f32_e32 v251, v109
	v_exp_f32_e32 v252, v110
	v_mfma_f32_32x32x16_bf16 v[16:31], v[132:135], v[96:99], v[16:31]
	v_exp_f32_e32 v253, v111
	v_add_f32_e32 v14, v15, v14
	v_cvt_pk_bf16_f32 v100, v246, v247
	v_cvt_pk_bf16_f32 v101, v248, v249
	v_cvt_pk_bf16_f32 v102, v250, v251
	v_add_f32_e32 v14, v240, v14
	v_cvt_pk_bf16_f32 v103, v252, v253
	v_add_f32_e32 v14, v241, v14
	s_barrier
; template <bool ONLINE, int NO>
; __device__ __forceinline__ void softmax_tile(f32x16 (&s)[2], float& m, float& l, f32x16 (&O)[NO], u32x4 (&pk)[4]) {
;     ...
;     float ps = 0.f;
; #pragma unroll
;     for (int blk = 0; blk < 2; ++blk)
; #pragma unroll
;         for (int i = 0; i < 16; ++i) { const float p = __builtin_amdgcn_exp2f(ONLINE ? (s[blk][i] - mn) : s[blk][i]); ps += p; s[blk][i] = p; }
;     l += ps;
; #pragma unroll
;     for (int blk = 0; blk < 2; ++blk)
; #pragma unroll
;         for (int sh = 0; sh < 2; ++sh) { u32x4 pw;
;             pw.x = cvt_pk_bf16(s[blk][8 * sh], s[blk][8 * sh + 1]); pw.y = cvt_pk_bf16(s[blk][8 * sh + 2], s[blk][8 * sh + 3]);
;             pw.z = cvt_pk_bf16(s[blk][8 * sh + 4], s[blk][8 * sh + 5]); pw.w = cvt_pk_bf16(s[blk][8 * sh + 6], s[blk][8 * sh + 7]); pk[2 * blk + sh] = pw; }
	s_waitcnt lgkmcnt(8)
	v_mfma_f32_32x32x16_bf16 v[64:79], v[168:171], v[100:103], v[64:79]
	ds_read_b64_tr_b16 v[144:145], v0 offset:0x3000
	ds_read_b64_tr_b16 v[146:147], v0 offset:0x3100
	ds_read_b64_tr_b16 v[140:141], v0 offset:0x3200
	ds_read_b64_tr_b16 v[142:143], v0 offset:0x3300
	ds_read_b64_tr_b16 v[136:137], v0 offset:0x3400
	ds_read_b64_tr_b16 v[138:139], v0 offset:0x3500
	ds_read_b64_tr_b16 v[132:133], v0 offset:0x3600
	ds_read_b64_tr_b16 v[134:135], v0 offset:0x3700
	v_mfma_f32_32x32x16_bf16 v[48:63], v[10:13], v[100:103], v[48:63]
	v_exp_f32_e32 v104, v80
	v_exp_f32_e32 v105, v81
	v_exp_f32_e32 v106, v82
	v_mfma_f32_32x32x16_bf16 v[32:47], v[180:183], v[100:103], v[32:47]
	v_exp_f32_e32 v107, v83
	v_exp_f32_e32 v108, v84
	v_exp_f32_e32 v109, v85
	v_mfma_f32_32x32x16_bf16 v[16:31], v[2:5], v[100:103], v[16:31]
	v_exp_f32_e32 v110, v86
	v_exp_f32_e32 v111, v87
	v_cvt_pk_bf16_f32 v80, v104, v105
	v_cvt_pk_bf16_f32 v81, v106, v107
	v_cvt_pk_bf16_f32 v82, v108, v109
	v_add_f32_e32 v14, v242, v14
	v_cvt_pk_bf16_f32 v83, v110, v111
	v_add_f32_e32 v14, v243, v14
	s_waitcnt lgkmcnt(8)
	v_mfma_f32_32x32x16_bf16 v[64:79], v[6:9], v[80:83], v[64:79]
	v_exp_f32_e32 v2, v88
	v_exp_f32_e32 v3, v89
	v_exp_f32_e32 v4, v90
	v_mfma_f32_32x32x16_bf16 v[48:63], v[128:131], v[80:83], v[48:63]
	v_exp_f32_e32 v5, v91
	v_exp_f32_e32 v10, v92
	v_exp_f32_e32 v11, v93
	v_mfma_f32_32x32x16_bf16 v[32:47], v[172:175], v[80:83], v[32:47]
	v_exp_f32_e32 v12, v94
	v_exp_f32_e32 v13, v95
	v_add_f32_e32 v14, v244, v14
	v_add_f32_e32 v14, v245, v14
	v_mfma_f32_32x32x16_bf16 v[16:31], v[184:187], v[80:83], v[16:31]
	v_cvt_pk_bf16_f32 v84, v2, v3
	v_cvt_pk_bf16_f32 v85, v4, v5
	v_cvt_pk_bf16_f32 v86, v10, v11
	v_add_f32_e32 v14, v246, v14
	v_cvt_pk_bf16_f32 v87, v12, v13
	v_add_f32_e32 v14, v247, v14
	v_add_f32_e32 v14, v248, v14
	s_waitcnt lgkmcnt(0)
	v_add_f32_e32 v14, v249, v14
	v_add_f32_e32 v14, v250, v14
	v_add_f32_e32 v14, v251, v14
	v_add_f32_e32 v14, v252, v14
	v_add_f32_e32 v14, v253, v14
	s_add_i32 s41, s40, 3
	s_cmp_ge_u32 s41, s22
	s_cbranch_scc1 .Lm1f_nodma
	s_cmpk_gt_u32 s58, 0xff
	s_cbranch_scc1 .Lm1f_nodma
	v_mfma_f32_32x32x16_bf16 v[64:79], v[144:147], v[84:87], v[64:79]
	s_mov_b64 s[70:71], 0x1000
	s_add_i32 s41, s38, 0x18000
	s_and_b32 s41, s41, 0x18000
	s_add_i32 s41, s77, s41
	v_lshl_add_u64 v[240:241], v[152:153], 0, s[68:69]
	v_lshl_add_u64 v[242:243], v[240:241], 0, s[42:43]
	s_mov_b32 m0, s41
	v_lshl_add_u64 v[240:241], v[240:241], 0, s[44:45]
	global_load_lds_dwordx4 v[242:243], off
	v_mfma_f32_32x32x16_bf16 v[48:63], v[140:143], v[84:87], v[48:63]
	s_add_i32 m0, s41, 0x1000
	v_lshl_add_u64 v[242:243], v[242:243], 0, s[70:71]
	global_load_lds_dwordx4 v[242:243], off
	s_add_i32 m0, s41, 0x2000
	v_lshl_add_u64 v[242:243], v[240:241], 0, s[70:71]
	global_load_lds_dwordx4 v[240:241], off
	s_add_i32 m0, s41, 0x3000
	v_lshl_add_u64 v[240:241], v[154:155], 0, s[68:69]
	global_load_lds_dwordx4 v[242:243], off
	v_add_f32_e32 v14, v104, v14
	v_add_f32_e32 v14, v105, v14
	v_add_f32_e32 v14, v106, v14
	v_add_f32_e32 v14, v107, v14
	v_mfma_f32_32x32x16_bf16 v[32:47], v[136:139], v[84:87], v[32:47]
	v_lshl_add_u64 v[242:243], v[240:241], 0, s[48:49]
	s_add_i32 m0, s41, 0x4000
	v_lshl_add_u64 v[240:241], v[240:241], 0, s[50:51]
	global_load_lds_dwordx4 v[242:243], off
	s_add_i32 m0, s41, 0x5000
	v_lshl_add_u64 v[242:243], v[242:243], 0, s[70:71]
	global_load_lds_dwordx4 v[242:243], off
	v_add_f32_e32 v14, v108, v14
	v_add_f32_e32 v14, v109, v14
	v_add_f32_e32 v14, v110, v14
	v_add_f32_e32 v14, v111, v14
	v_add_f32_e32 v14, v2, v14
	v_add_f32_e32 v14, v3, v14
	v_mfma_f32_32x32x16_bf16 v[16:31], v[132:135], v[84:87], v[16:31]
	s_add_i32 m0, s41, 0x6000
	v_lshl_add_u64 v[242:243], v[240:241], 0, s[70:71]
	global_load_lds_dwordx4 v[240:241], off
	s_add_i32 m0, s41, 0x7000
	s_nop 0
	global_load_lds_dwordx4 v[242:243], off
	v_add_f32_e32 v14, v4, v14
	v_add_f32_e32 v14, v5, v14
	v_add_f32_e32 v14, v10, v14
	v_add_f32_e32 v14, v11, v14
	v_add_f32_e32 v14, v12, v14
	v_add_f32_e32 v14, v13, v14
	v_add_f32_e32 v163, v163, v14
	s_branch .LBB0_474
.Lm1f_nodma:
	v_mfma_f32_32x32x16_bf16 v[64:79], v[144:147], v[84:87], v[64:79]
	v_add_f32_e32 v14, v104, v14
	v_add_f32_e32 v14, v105, v14
	v_add_f32_e32 v14, v106, v14
	v_add_f32_e32 v14, v107, v14
	v_add_f32_e32 v14, v108, v14
	v_add_f32_e32 v14, v109, v14
	v_mfma_f32_32x32x16_bf16 v[48:63], v[140:143], v[84:87], v[48:63]
	v_add_f32_e32 v14, v110, v14
	v_add_f32_e32 v14, v111, v14
	v_add_f32_e32 v14, v2, v14
	v_add_f32_e32 v14, v3, v14
	v_add_f32_e32 v14, v4, v14
	v_add_f32_e32 v14, v5, v14
	v_mfma_f32_32x32x16_bf16 v[32:47], v[136:139], v[84:87], v[32:47]
	v_add_f32_e32 v14, v10, v14
	v_add_f32_e32 v14, v11, v14
	v_add_f32_e32 v14, v12, v14
	v_add_f32_e32 v14, v13, v14
	v_add_f32_e32 v163, v163, v14
	v_mfma_f32_32x32x16_bf16 v[16:31], v[132:135], v[84:87], v[16:31]
	s_branch .LBB0_474

; template <int MODE>
; __device__ __forceinline__ void attn_unit(const Params& P, LAS unsigned char* lds, const int b, const int h, const int qb) {
;     ...
;             if constexpr (MODE == 1) {
;                 bf16x8 kf[8];
;                 const unsigned kb_ = (unsigned)(uintptr_t)Kb + kra, c0 = mp * 8 + hh;
;                 k_issue4(kf, kb_ + (((c0) ^ kswz) << 4), kb_ + (((c0 + 2) ^ kswz) << 4), kb_ + (((c0 + 4) ^ kswz) << 4), kb_ + (((c0 + 6) ^ kswz) << 4));
;                 v_issue<0>(va, vaddr);
;                 k_wait<8>(kf);
; #pragma unroll
;                 for (int ks = 0; ks < 4; ++ks) { s[0] = MFMA32(kf[2 * ks], Qf[ks], s[0]); s[1] = MFMA32(kf[2 * ks + 1], Qf[ks], s[1]); }
;                 v_issue<1>(vb, vaddr);
;             } else {
; #pragma unroll
;             for (int ks = 0; ks < NQ; ++ks) {
;                 const unsigned chunk = mp * 8 + 2 * ks + hh;
;                 const unsigned off = kra + ((chunk ^ kswz) << 4);
;                 const bf16x8 a0 = *(const LAS bf16x8*)(Kb + off), a1 = *(const LAS bf16x8*)(Kb + off + 8192);
;                 s[0] = MFMA32(a0, Qf[ks], s[0]); s[1] = MFMA32(a1, Qf[ks], s[1]);
;             }
;             v_issue<0>(va, vaddr);
;             }
;             if (FOX) {
;                 const LAS float* cl = (const LAS float*)(lds + AL_CLS + (cur * 8 + w) * 256) + 8 * hh;
; #pragma unroll
;                 for (int blk = 0; blk < 2; ++blk)
; #pragma unroll
;                     for (int j4 = 0; j4 < 4; ++j4) { const f32x4 c = *(const LAS f32x4*)(cl + 32 * blk + 16 * (j4 >> 1) + 4 * (j4 & 1));
; #pragma unroll
;                         for (int e = 0; e < 4; ++e) s[blk][4 * j4 + e] -= c[e]; }
;             } else if (q0w - kt * 64 - 63 < 128) {
;                 const LAS float* bl = (const LAS float*)(lds + AL_BIAS);
; #pragma unroll
;                 for (int blk = 0; blk < 2; ++blk)
; #pragma unroll
;                     for (int i = 0; i < 16; ++i) { const int dist = q - (kbase + 32 * blk + 16 * (i >> 3) + (i & 7)); const int di = dist < 0 ? 0 : (dist > 128 ? 128 : dist); s[blk][i] += bl[di]; }
;             }
;             if (kt * 64 + 63 > q0w) {
; #pragma unroll
;                 for (int blk = 0; blk < 2; ++blk)
; #pragma unroll
;                     for (int i = 0; i < 16; ++i) { if (kbase + 32 * blk + 16 * (i >> 3) + (i & 7) > q) s[blk][i] = -INFINITY; }
;             }
.Lm1_fastB:
	v_mfma_f32_32x32x16_bf16 v[96:111], v[2:5], v[112:115], 0
	v_mfma_f32_32x32x16_bf16 v[96:111], v[10:13], v[116:119], v[96:111]
	v_mfma_f32_32x32x16_bf16 v[96:111], v[168:171], v[120:123], v[96:111]
	v_mfma_f32_32x32x16_bf16 v[96:111], v[180:183], v[124:127], v[96:111]
	ds_read_b64_tr_b16 v[168:169], v0 offset:0x1000
	ds_read_b64_tr_b16 v[170:171], v0 offset:0x1100
	ds_read_b64_tr_b16 v[10:11], v0 offset:0x1200
	ds_read_b64_tr_b16 v[12:13], v0 offset:0x1300
	ds_read_b64_tr_b16 v[180:181], v0 offset:0x1400
	ds_read_b64_tr_b16 v[182:183], v0 offset:0x1500
	ds_read_b64_tr_b16 v[2:3], v0 offset:0x1600
	ds_read_b64_tr_b16 v[4:5], v0 offset:0x1700
	v_mfma_f32_32x32x16_bf16 v[80:95], v[6:9], v[112:115], 0
	s_nop 2
	v_exp_f32_e32 v14, v96
	v_exp_f32_e32 v15, v97
	v_mfma_f32_32x32x16_bf16 v[80:95], v[128:131], v[116:119], v[80:95]
	v_exp_f32_e32 v240, v98
	v_exp_f32_e32 v241, v99
	v_exp_f32_e32 v242, v100
	v_mfma_f32_32x32x16_bf16 v[80:95], v[172:175], v[120:123], v[80:95]
	v_exp_f32_e32 v243, v101
	v_exp_f32_e32 v244, v102
	v_exp_f32_e32 v245, v103
	v_mfma_f32_32x32x16_bf16 v[80:95], v[184:187], v[124:127], v[80:95]
	v_cvt_pk_bf16_f32 v96, v14, v15
	v_cvt_pk_bf16_f32 v97, v240, v241
	v_cvt_pk_bf16_f32 v98, v242, v243
	v_cvt_pk_bf16_f32 v99, v244, v245
	v_exp_f32_e32 v246, v104
	s_waitcnt lgkmcnt(8)
	v_mfma_f32_32x32x16_bf16 v[64:79], v[144:147], v[96:99], v[64:79]
	ds_read_b64_tr_b16 v[6:7], v0 offset:0x2000
	ds_read_b64_tr_b16 v[8:9], v0 offset:0x2100
	ds_read_b64_tr_b16 v[128:129], v0 offset:0x2200
	ds_read_b64_tr_b16 v[130:131], v0 offset:0x2300
	ds_read_b64_tr_b16 v[172:173], v0 offset:0x2400
	ds_read_b64_tr_b16 v[174:175], v0 offset:0x2500
	ds_read_b64_tr_b16 v[184:185], v0 offset:0x2600
	ds_read_b64_tr_b16 v[186:187], v0 offset:0x2700
	v_mfma_f32_32x32x16_bf16 v[48:63], v[140:143], v[96:99], v[48:63]
	v_exp_f32_e32 v247, v105
	v_exp_f32_e32 v248, v106
	v_exp_f32_e32 v249, v107
	v_mfma_f32_32x32x16_bf16 v[32:47], v[136:139], v[96:99], v[32:47]
	v_exp_f32_e32 v250, v108
	v_exp_f32_e32 v251, v109
	v_exp_f32_e32 v252, v110
	v_mfma_f32_32x32x16_bf16 v[16:31], v[132:135], v[96:99], v[16:31]
	v_exp_f32_e32 v253, v111
	v_add_f32_e32 v14, v15, v14
	v_cvt_pk_bf16_f32 v100, v246, v247
	v_cvt_pk_bf16_f32 v101, v248, v249
	v_cvt_pk_bf16_f32 v102, v250, v251
	v_add_f32_e32 v14, v240, v14
	v_cvt_pk_bf16_f32 v103, v252, v253
	v_add_f32_e32 v14, v241, v14
	s_branch .LBB0_474
